# plus: the P8 idle workgroups also use the pipelined collective copy engine (16 groups per grab)
# speedup vs baseline: 1.0014x; 1.0014x over previous
.LBB0_2096:
	s_cmp_lt_i32 s72, 9
	s_cselect_b64 s[0:1], -1, 0
	s_cmp_gt_i32 s73, 8
	s_cselect_b64 s[4:5], -1, 0
	s_and_b64 s[0:1], s[0:1], s[4:5]
	s_andn2_b64 vcc, exec, s[0:1]
	s_cbranch_vccnz .LBB0_2179
	s_and_b64 s[0:1], s[58:59], exec
	v_readlane_b32 s4, v242, 2
	s_cselect_b32 s33, 0xb0, s84
	v_mov_b32_e32 v149, 0
	v_readlane_b32 s5, v242, 3
	s_cmp_ge_i32 s92, s33
	v_readlane_b32 s6, v242, 4
	v_lshl_add_u64 v[128:129], s[4:5], 0, v[148:149]
	s_mov_b64 s[4:5], -1
	v_readlane_b32 s7, v242, 5
	s_cbranch_scc0 .LBB0_2131
	v_mov_b32_e32 v104, v148
	v_add_u32_e32 v105, 0x2000, v104
	v_add_u32_e32 v106, 0x4000, v104
	v_add_u32_e32 v107, 0x6000, v104
	v_add_u32_e32 v108, 0x8000, v104
	v_add_u32_e32 v109, 0xa000, v104
	v_add_u32_e32 v110, 0xc000, v104
	v_add_u32_e32 v111, 0xe000, v104
	v_add_u32_e32 v112, 0x10000, v104
	v_add_u32_e32 v113, 0x12000, v104
	v_add_u32_e32 v114, 0x14000, v104
	v_add_u32_e32 v115, 0x16000, v104
	v_add_u32_e32 v116, 0x18000, v104
	v_add_u32_e32 v117, 0x1a000, v104
	v_add_u32_e32 v118, 0x1c000, v104
	v_add_u32_e32 v119, 0x1e000, v104
	v_lshrrev_b32_e32 v5, 10, v148
	v_readlane_b32 s56, v242, 43
	v_readlane_b32 s57, v242, 44
	v_readlane_b32 s60, v242, 2
	v_readlane_b32 s61, v242, 3
	v_readlane_b32 s66, v242, 4
	v_readlane_b32 s67, v242, 5
	v_readlane_b32 s68, v242, 25
	v_readfirstlane_b32 s70, v5
	v_mov_b32_e32 v2, 0
	v_mov_b32_e32 v3, 16
	v_mov_b32_e32 v6, 0x20180
	s_mov_b32 s64, 0x10478000
	s_mov_b32 s65, 0x30478000
	s_add_u32 s66, s66, 0x5400
	s_addc_u32 s67, s67, 0
	v_readlane_b32 s69, v242, 57
	s_nop 3
	s_mul_i32 s68, s68, s69
	s_mov_b64 s[62:63], exec
	s_mov_b32 s71, 0
	s_cmp_lg_u32 s70, 0
	s_cbranch_scc1 .Lce_first_done_P8
	s_mov_b64 exec, 1
	global_atomic_add v4, v2, v3, s[56:57] sc0
	s_waitcnt vmcnt(0)
	ds_write_b32 v6, v4
	s_waitcnt lgkmcnt(0)
	s_mov_b64 exec, s[62:63]
